# comb6: + relaxed first-iteration vmcnt at GU tile transitions (epilogue stores stay in flight across kt=1)
# speedup vs baseline: 1.0538x; 1.0027x over previous
.LBB0_91:
	s_andn2_saveexec_b64 s[0:1], s[8:9]
	s_cbranch_execz .LBB0_111
	s_mov_b64 s[8:9], exec
	s_nop 0
	s_waitcnt lgkmcnt(0)
	s_waitcnt vmcnt(0)
	v_mbcnt_lo_u32_b32 v1, s8, 0
	v_mbcnt_hi_u32_b32 v1, s9, v1
	v_cmp_eq_u32_e32 vcc, 0, v1
	s_and_saveexec_b64 s[10:11], vcc
	s_cbranch_execz .LBB0_94
	s_bcnt1_i32_b64 s0, s[8:9]
	v_mov_b32_e32 v2, 0x2b000
	v_mov_b32_e32 v3, s0
	global_atomic_add v2, v2, v3, s[56:57] offset:1024 sc0

.LBB0_629:
	s_or_b64 exec, exec, s[4:5]
	s_cmpk_lt_i32 s78, 0x580
	s_cselect_b64 s[0:1], -1, 0
	v_writelane_b32 v219, s0, 52
	s_cmpk_gt_i32 s78, 0x57f
	v_readfirstlane_b32 s4, v168
	s_waitcnt lgkmcnt(0)
	s_barrier
	v_mov_b32_e32 v222, 0
	v_writelane_b32 v219, s1, 53
	s_cbranch_scc1 .LBB0_693
	s_add_u32 s0, s56, 0x900000
	s_addc_u32 s1, s57, 0
	s_lshl_b32 s2, s78, 19
	s_lshr_b32 s5, s4, 6
	s_bfe_u32 s22, s4, 0x10006
	s_lshr_b32 s23, s4, 7
	s_and_b32 s2, s2, 0xf80000
	s_add_u32 s16, s30, s2
	s_addc_u32 s17, s31, 0
	s_lshl_b32 s2, s78, 2
	s_and_b32 s2, s2, 0xffffff80
	s_ashr_i32 s3, s2, 31
	s_mov_b32 s93, 0
	s_lshl_b64 s[6:7], s[2:3], 11
	s_lshl_b32 s92, s5, 5
	s_lshl_b32 s2, s5, 12
	s_add_i32 s3, s2, 0
	s_lshl_b64 s[14:15], s[92:93], 11
	s_add_u32 s8, s16, s14
	s_addc_u32 s9, s17, s15
	s_or_b32 s10, s92, 8
	s_mov_b32 s11, s93
	s_lshl_b64 s[36:37], s[10:11], 11
	s_add_u32 s10, s16, s36
	v_mov_b32_e32 v0, v178
	v_mov_b32_e32 v1, v179
	s_mov_b32 m0, s3
	s_addc_u32 s11, s17, s37
	s_or_b32 s12, s92, 16
	s_mov_b32 s13, s93
	s_barrier
	s_lshl_b64 s[38:39], s[12:13], 11
	global_load_lds_dwordx4 v0, s[8:9]
	s_add_i32 m0, s3, 0x400
	s_add_u32 s12, s16, s38
	s_addc_u32 s13, s17, s39
	s_or_b32 s92, s92, 24
	global_load_lds_dwordx4 v1, s[10:11]
	s_add_i32 m0, s3, 0x800
	s_lshl_b64 s[40:41], s[92:93], 11
	s_add_u32 s18, s16, s40
	global_load_lds_dwordx4 v0, s[12:13]
	s_addc_u32 s19, s17, s41
	s_add_i32 m0, s3, 0xc00
	s_add_u32 s17, s0, s6
	s_addc_u32 s21, s1, s7
	s_lshl_b32 s16, s5, 11
	s_lshl_b32 s92, s5, 4
	s_sub_i32 s24, s3, s16
	global_load_lds_dwordx4 v1, s[18:19]
	s_add_i32 m0, s24, 0x8000
	s_lshl_b64 s[42:43], s[92:93], 11
	s_add_u32 s6, s17, s42
	s_addc_u32 s7, s21, s43
	s_or_b32 s92, s92, 8
	s_lshl_b64 s[44:45], s[92:93], 11
	s_add_u32 s20, s17, s44
	global_load_lds_dwordx4 v0, s[6:7]
	s_addc_u32 s21, s21, s45
	s_add_i32 m0, s24, 0x8400
	v_mov_b32_e32 v150, v178
	v_mov_b32_e32 v0, v179
	v_mov_b32_e32 v151, 0
	global_load_lds_dwordx4 v1, s[20:21]
	s_mov_b64 s[46:47], 0x80
	v_lshl_add_u64 v[2:3], s[8:9], 0, v[150:151]
	s_add_i32 m0, s3, 0xc000
	v_lshl_add_u64 v[2:3], v[2:3], 0, s[46:47]
	v_mov_b32_e32 v1, v151
	global_load_lds_dwordx4 v[2:3], off
	v_lshl_add_u64 v[2:3], s[10:11], 0, v[0:1]
	v_lshl_add_u64 v[2:3], v[2:3], 0, s[46:47]
	s_add_i32 m0, s3, 0xc400
	s_add_i32 s8, s16, 0
	global_load_lds_dwordx4 v[2:3], off
	v_lshl_add_u64 v[2:3], s[12:13], 0, v[150:151]
	v_lshl_add_u64 v[2:3], v[2:3], 0, s[46:47]
	s_add_i32 m0, s3, 0xc800
	v_lshl_or_b32 v156, s23, 6, v167
	global_load_lds_dwordx4 v[2:3], off
	v_lshl_add_u64 v[2:3], s[18:19], 0, v[0:1]
	v_lshl_add_u64 v[2:3], v[2:3], 0, s[46:47]
	s_add_i32 m0, s3, 0xcc00
	v_lshl_add_u64 v[0:1], s[20:21], 0, v[0:1]
	global_load_lds_dwordx4 v[2:3], off
	v_lshl_add_u64 v[2:3], s[6:7], 0, v[150:151]
	s_add_i32 m0, s8, 0x14000
	v_lshl_add_u64 v[2:3], v[2:3], 0, s[46:47]
	global_load_lds_dwordx4 v[2:3], off
	v_lshl_add_u64 v[0:1], v[0:1], 0, s[46:47]
	s_add_i32 m0, s8, 0x14400
	s_cmpk_gt_u32 s4, 0xff
	global_load_lds_dwordx4 v[0:1], off
	s_cselect_b64 s[48:49], -1, 0
	s_lshl_b32 s92, s5, 15
	s_lshl_b32 s4, s5, 14
	s_lshl_b32 s17, s22, 13
	s_lshl_b32 s18, s23, 13
	s_lshl_b32 s6, s22, 6
	v_readlane_b32 s8, v219, 33
	v_readlane_b32 s9, v219, 34
	s_add_u32 s6, s8, s6
	s_addc_u32 s7, s9, 0
	s_add_u32 s19, s56, s14
	s_addc_u32 s22, s57, s15
	s_lshl_b32 s23, s78, 8
	s_lshl_b32 s24, s58, 8
	s_add_u32 s25, s56, s42
	s_addc_u32 s26, s57, s43
	s_lshl_b64 s[50:51], s[92:93], 1
	s_mov_b32 s5, s93
	v_add_u32_e32 v0, 12, v146
	v_cmp_eq_u32_e32 vcc, 0, v171
	s_add_u32 s27, s56, s50
	v_xor_b32_e32 v1, v147, v170
	v_cndmask_b32_e32 v0, v0, v146, vcc
	s_addc_u32 s28, s57, s51
	s_lshl_b64 s[68:69], s[4:5], 1
	v_lshlrev_b32_e32 v157, 4, v1
	v_bitop3_b32 v1, v147, v170, 4 bitop3:0x36
	v_lshlrev_b32_e32 v150, 1, v0
	s_add_u32 s29, s56, s68
	v_lshlrev_b32_e32 v158, 4, v1
	v_lshl_add_u64 v[152:153], s[6:7], 0, v[150:151]
	s_addc_u32 s33, s57, s69
	s_mov_b64 s[4:5], -1
	s_mov_b64 s[70:71], 0x100
	s_mov_b64 s[72:73], 0x3400180
	s_mov_b64 s[74:75], 0x3404180
	s_mov_b64 s[76:77], 0x3408180
	s_mov_b32 s61, s78
	s_mov_b64 s[78:79], 0x340c180
	s_mov_b64 s[80:81], 0x900180
	s_mov_b64 s[82:83], 0x904180
	s_mov_b64 s[84:85], 0x4000
	s_movk_i32 s60, 0x1600
	s_branch .LBB0_632

.LBB0_640:
	v_readfirstlane_b32 s100, v222
	s_nop 1
	s_cmp_eq_u32 s100, 1
	s_cbranch_scc1 .Lrw640_a
	s_waitcnt vmcnt(6) lgkmcnt(0)
	s_branch .Lrw640_d
.Lrw640_a:
	s_waitcnt vmcnt(10) lgkmcnt(0)
	v_mov_b32_e32 v222, 2
.Lrw640_d:
	s_barrier
	s_waitcnt lgkmcnt(0)
	v_mfma_f32_16x16x32_bf16 v[124:127], v[52:55], v[64:67], v[124:127]
	s_mul_i32 s86, s97, 0xc000
	s_add_i32 s87, s86, 0xffff4000
	v_mfma_f32_16x16x32_bf16 v[120:123], v[48:51], v[64:67], v[120:123]
	s_cmp_lg_u32 s97, 0
	s_cselect_b32 s87, s87, 0x18000
	s_add_i32 s84, s3, s87
	v_mfma_f32_16x16x32_bf16 v[116:119], v[44:47], v[64:67], v[116:119]
	v_mfma_f32_16x16x32_bf16 v[64:67], v[40:43], v[64:67], v[112:115]
	v_mfma_f32_16x16x32_bf16 v[108:111], v[52:55], v[56:59], v[108:111]
	v_mfma_f32_16x16x32_bf16 v[104:107], v[48:51], v[56:59], v[104:107]
	v_mfma_f32_16x16x32_bf16 v[100:103], v[44:47], v[56:59], v[100:103]
	v_mfma_f32_16x16x32_bf16 v[56:59], v[40:43], v[56:59], v[96:99]
	s_add_u32 s88, s10, s6
	v_mov_b32_e32 v150, v178
	s_addc_u32 s89, s11, s7
	s_mov_b32 m0, s84
	s_add_u32 s98, s88, s72
	s_addc_u32 s99, s89, s73
	global_load_lds_dwordx4 v178, s[98:99]
	v_mfma_f32_16x16x32_bf16 v[92:95], v[52:55], v[36:39], v[92:95]
	v_mfma_f32_16x16x32_bf16 v[88:91], v[48:51], v[36:39], v[88:91]
	v_mfma_f32_16x16x32_bf16 v[84:87], v[44:47], v[36:39], v[84:87]
	v_mfma_f32_16x16x32_bf16 v[36:39], v[40:43], v[36:39], v[80:83]
	v_mfma_f32_16x16x32_bf16 v[52:55], v[52:55], v[32:35], v[76:79]
	v_mfma_f32_16x16x32_bf16 v[48:51], v[48:51], v[32:35], v[72:75]
	v_mfma_f32_16x16x32_bf16 v[44:47], v[44:47], v[32:35], v[68:71]
	v_mfma_f32_16x16x32_bf16 v[32:35], v[40:43], v[32:35], v[60:63]
	v_mov_b32_e32 v150, v179
	s_add_i32 m0, s84, 0x400
	s_add_u32 s100, s88, s74
	s_addc_u32 s101, s89, s75
	global_load_lds_dwordx4 v179, s[100:101]
	v_mfma_f32_16x16x32_bf16 v[124:127], v[20:23], v[28:31], v[124:127]
	v_mfma_f32_16x16x32_bf16 v[120:123], v[16:19], v[28:31], v[120:123]
	v_mfma_f32_16x16x32_bf16 v[116:119], v[12:15], v[28:31], v[116:119]
	v_mfma_f32_16x16x32_bf16 v[112:115], v[8:11], v[28:31], v[64:67]
	v_mfma_f32_16x16x32_bf16 v[108:111], v[20:23], v[24:27], v[108:111]
	v_mfma_f32_16x16x32_bf16 v[104:107], v[16:19], v[24:27], v[104:107]
	v_mfma_f32_16x16x32_bf16 v[100:103], v[12:15], v[24:27], v[100:103]
	v_mfma_f32_16x16x32_bf16 v[96:99], v[8:11], v[24:27], v[56:59]
	v_mov_b32_e32 v150, v178
	s_add_i32 m0, s84, 0x800
	s_add_u32 s98, s88, s76
	s_addc_u32 s99, s89, s77
	global_load_lds_dwordx4 v178, s[98:99]
	v_mfma_f32_16x16x32_bf16 v[92:95], v[20:23], v[4:7], v[92:95]
	s_waitcnt lgkmcnt(0)
	v_mfma_f32_16x16x32_bf16 v[88:91], v[16:19], v[4:7], v[88:91]
	v_mfma_f32_16x16x32_bf16 v[84:87], v[12:15], v[4:7], v[84:87]
	v_mfma_f32_16x16x32_bf16 v[80:83], v[8:11], v[4:7], v[36:39]
	v_mfma_f32_16x16x32_bf16 v[76:79], v[20:23], v[0:3], v[52:55]
	v_mfma_f32_16x16x32_bf16 v[72:75], v[16:19], v[0:3], v[48:51]
	v_mfma_f32_16x16x32_bf16 v[68:71], v[12:15], v[0:3], v[44:47]
	v_mfma_f32_16x16x32_bf16 v[60:63], v[8:11], v[0:3], v[32:35]
	s_barrier
	s_add_i32 s84, s86, 0
	v_add_u32_e32 v0, s84, v157
	v_add_u32_e32 v8, s84, v158
	s_add_i32 s84, s87, 0
	s_add_i32 s85, s84, s2
	s_add_i32 m0, s85, 0xc00
	s_add_u32 s100, s88, s78
	s_addc_u32 s101, s89, s79
	s_add_u32 s88, vcc_lo, s6
	s_addc_u32 s89, vcc_hi, s7
	global_load_lds_dwordx4 v179, s[100:101]
	s_add_i32 s84, s84, s16
	s_add_i32 m0, s84, 0x8000
	s_add_u32 s98, s88, s80
	s_addc_u32 s99, s89, s81
	global_load_lds_dwordx4 v178, s[98:99]
	s_add_i32 m0, s84, 0x8400
	s_add_u32 s100, s88, s82
	s_addc_u32 s101, s89, s83
	global_load_lds_dwordx4 v179, s[100:101]
	v_add3_u32 v1, v0, s18, v169
	v_add3_u32 v0, v0, s17, v169
	ds_read_b128 v[64:67], v1
	ds_read_b128 v[56:59], v1 offset:2048
	ds_read_b128 v[36:39], v1 offset:4096
	ds_read_b128 v[32:35], v1 offset:6144
	ds_read_b128 v[52:55], v0 offset:32768
	ds_read_b128 v[48:51], v0 offset:34816
	ds_read_b128 v[44:47], v0 offset:36864
	ds_read_b128 v[40:43], v0 offset:38912
	v_add3_u32 v0, v8, s18, v169
	v_add3_u32 v8, v8, s17, v169
	ds_read_b128 v[28:31], v0
	ds_read_b128 v[24:27], v0 offset:2048
	ds_read_b128 v[4:7], v0 offset:4096
	ds_read_b128 v[0:3], v0 offset:6144
	ds_read_b128 v[20:23], v8 offset:32768
	ds_read_b128 v[16:19], v8 offset:34816
	ds_read_b128 v[12:15], v8 offset:36864
	ds_read_b128 v[8:11], v8 offset:38912
	s_waitcnt lgkmcnt(0)
	v_mov_b32_e32 v150, v179
	v_mov_b32_e32 v150, v178
	v_mov_b32_e32 v150, v179
	s_add_i32 s84, s97, 1
	s_cmp_lg_u32 s97, 2
	s_cselect_b32 s97, s84, 0
	s_add_u32 s6, s6, 0x80
	s_addc_u32 s7, s7, 0
	s_cmpk_eq_i32 s6, 0x680
	s_cbranch_scc0 .LBB0_640
	v_mov_b32_e32 v222, 1
	s_waitcnt vmcnt(6) lgkmcnt(0)
	s_barrier
	s_waitcnt lgkmcnt(0)
	v_mfma_f32_16x16x32_bf16 v[124:127], v[52:55], v[64:67], v[124:127]
	s_mul_i32 s11, s97, 0xc000
	s_add_i32 s6, s11, 0xffff4000
	v_mfma_f32_16x16x32_bf16 v[120:123], v[48:51], v[64:67], v[120:123]
	s_cmp_lg_u32 s97, 0
	s_cselect_b32 s10, s6, 0x18000
	s_andn2_b64 vcc, exec, s[94:95]
	v_mfma_f32_16x16x32_bf16 v[116:119], v[44:47], v[64:67], v[116:119]
	v_mfma_f32_16x16x32_bf16 v[64:67], v[40:43], v[64:67], v[112:115]
	v_mfma_f32_16x16x32_bf16 v[108:111], v[52:55], v[56:59], v[108:111]
	s_nop 1
	v_cndmask_b32_e64 v112, 0, 1, s[94:95]
	v_cmp_ne_u32_e64 s[6:7], 1, v112
	v_mfma_f32_16x16x32_bf16 v[104:107], v[48:51], v[56:59], v[104:107]
	v_mfma_f32_16x16x32_bf16 v[100:103], v[44:47], v[56:59], v[100:103]
	v_mfma_f32_16x16x32_bf16 v[140:143], v[40:43], v[56:59], v[96:99]
	s_cbranch_vccnz .LBB0_643
	s_add_u32 s88, s64, s14
	v_mov_b32_e32 v56, v178
	s_addc_u32 s89, s65, s15
	s_add_i32 m0, s3, s10
	s_nop 0
	global_load_lds_dwordx4 v56, s[88:89]

.Lrw667_d:
	s_barrier
	s_mul_i32 s13, s10, 0xc000
	s_add_i32 s20, s13, 0
	v_add_u32_e32 v80, s20, v157
	v_add_u32_e32 v112, s20, v158
	s_add_i32 s13, s13, 0xffff4000
	s_cmp_lg_u32 s10, 0
	s_cselect_b32 s13, s13, 0x18000
	s_add_i32 s88, s13, 0
	s_add_u32 s20, s6, s4
	s_addc_u32 s21, s7, s5
	s_add_i32 s66, s88, s2
	s_add_i32 m0, s66, 0xc00
	s_add_u32 s66, s11, s4
	s_addc_u32 s67, s12, s5
	s_add_u32 s98, s20, s78
	s_addc_u32 s99, s21, s79
	global_load_lds_dwordx4 v179, s[98:99]
	s_add_i32 s88, s88, s16
	s_add_i32 m0, s88, 0x8000
	s_add_u32 s100, s66, s80
	s_addc_u32 s101, s67, s81
	global_load_lds_dwordx4 v178, s[100:101]
	s_add_i32 m0, s88, 0x8400
	s_add_u32 s98, s66, s82
	s_addc_u32 s99, s67, s83
	global_load_lds_dwordx4 v179, s[98:99]
	v_add3_u32 v76, v80, s18, v169
	v_add3_u32 v92, v80, s17, v169
	v_add3_u32 v108, v112, s18, v169
	v_add3_u32 v124, v112, s17, v169
	ds_read_b128 v[64:67], v76
	ds_read_b128 v[68:71], v76 offset:2048
	ds_read_b128 v[72:75], v76 offset:4096
	ds_read_b128 v[76:79], v76 offset:6144
	ds_read_b128 v[80:83], v92 offset:32768
	ds_read_b128 v[84:87], v92 offset:34816
	ds_read_b128 v[88:91], v92 offset:36864
	ds_read_b128 v[92:95], v92 offset:38912
	ds_read_b128 v[96:99], v108
	ds_read_b128 v[100:103], v108 offset:2048
	ds_read_b128 v[104:107], v108 offset:4096
	ds_read_b128 v[108:111], v108 offset:6144
	ds_read_b128 v[112:115], v124 offset:32768
	ds_read_b128 v[116:119], v124 offset:34816
	ds_read_b128 v[120:123], v124 offset:36864
	ds_read_b128 v[124:127], v124 offset:38912
	s_waitcnt lgkmcnt(0)
	v_mov_b32_e32 v150, v179
	v_mov_b32_e32 v150, v178
	v_mov_b32_e32 v150, v179
	s_waitcnt lgkmcnt(0)
	s_barrier
	s_waitcnt lgkmcnt(0)
	v_mfma_f32_16x16x32_bf16 v[60:63], v[80:83], v[64:67], v[60:63]
	s_add_i32 s13, s3, s13
	v_mfma_f32_16x16x32_bf16 v[56:59], v[84:87], v[64:67], v[56:59]
	v_mfma_f32_16x16x32_bf16 v[52:55], v[88:91], v[64:67], v[52:55]
	v_mfma_f32_16x16x32_bf16 v[48:51], v[92:95], v[64:67], v[48:51]
	v_mfma_f32_16x16x32_bf16 v[44:47], v[80:83], v[68:71], v[44:47]
	v_mfma_f32_16x16x32_bf16 v[40:43], v[84:87], v[68:71], v[40:43]
	v_mfma_f32_16x16x32_bf16 v[36:39], v[88:91], v[68:71], v[36:39]
	v_mfma_f32_16x16x32_bf16 v[24:27], v[92:95], v[68:71], v[24:27]
	v_mov_b32_e32 v150, v178
	s_mov_b32 m0, s13
	s_add_u32 s100, s20, s72
	s_addc_u32 s101, s21, s73
	global_load_lds_dwordx4 v178, s[100:101]
	v_mfma_f32_16x16x32_bf16 v[20:23], v[80:83], v[72:75], v[20:23]
	v_mfma_f32_16x16x32_bf16 v[16:19], v[84:87], v[72:75], v[16:19]
	v_mfma_f32_16x16x32_bf16 v[12:15], v[88:91], v[72:75], v[12:15]
	v_mfma_f32_16x16x32_bf16 v[8:11], v[92:95], v[72:75], v[8:11]
	v_mfma_f32_16x16x32_bf16 v[4:7], v[80:83], v[76:79], v[4:7]
	v_mfma_f32_16x16x32_bf16 v[0:3], v[84:87], v[76:79], v[0:3]
	v_mfma_f32_16x16x32_bf16 v[28:31], v[88:91], v[76:79], v[28:31]
	v_mfma_f32_16x16x32_bf16 v[32:35], v[92:95], v[76:79], v[32:35]
	v_mov_b32_e32 v150, v179
	s_add_i32 m0, s13, 0x400
	s_add_u32 s98, s20, s74
	s_addc_u32 s99, s21, s75
	global_load_lds_dwordx4 v179, s[98:99]
	v_mfma_f32_16x16x32_bf16 v[60:63], v[112:115], v[96:99], v[60:63]
	v_mfma_f32_16x16x32_bf16 v[56:59], v[116:119], v[96:99], v[56:59]
	v_mfma_f32_16x16x32_bf16 v[52:55], v[120:123], v[96:99], v[52:55]
	v_mfma_f32_16x16x32_bf16 v[48:51], v[124:127], v[96:99], v[48:51]
	v_mfma_f32_16x16x32_bf16 v[44:47], v[112:115], v[100:103], v[44:47]
	v_mfma_f32_16x16x32_bf16 v[40:43], v[116:119], v[100:103], v[40:43]
	v_mfma_f32_16x16x32_bf16 v[36:39], v[120:123], v[100:103], v[36:39]
	v_mfma_f32_16x16x32_bf16 v[24:27], v[124:127], v[100:103], v[24:27]
	v_mov_b32_e32 v150, v178
	s_add_i32 m0, s13, 0x800
	s_add_u32 s100, s20, s76
	s_addc_u32 s101, s21, s77
	global_load_lds_dwordx4 v178, s[100:101]
	s_add_i32 s13, s10, 1
	v_mfma_f32_16x16x32_bf16 v[20:23], v[112:115], v[104:107], v[20:23]
	s_cmp_lg_u32 s10, 2
	s_cselect_b32 s10, s13, 0
	s_add_u32 s4, s4, 0x80
	v_mfma_f32_16x16x32_bf16 v[16:19], v[116:119], v[104:107], v[16:19]
	s_addc_u32 s5, s5, 0
	s_cmpk_eq_i32 s4, 0x680
	v_mfma_f32_16x16x32_bf16 v[12:15], v[120:123], v[104:107], v[12:15]
	v_mfma_f32_16x16x32_bf16 v[8:11], v[124:127], v[104:107], v[8:11]
	v_mfma_f32_16x16x32_bf16 v[4:7], v[112:115], v[108:111], v[4:7]
	v_mfma_f32_16x16x32_bf16 v[0:3], v[116:119], v[108:111], v[0:3]
	v_mfma_f32_16x16x32_bf16 v[28:31], v[120:123], v[108:111], v[28:31]
	v_mfma_f32_16x16x32_bf16 v[32:35], v[124:127], v[108:111], v[32:35]
	s_cbranch_scc0 .LBB0_667
	v_mov_b32_e32 v222, 1
	s_waitcnt vmcnt(6) lgkmcnt(0)
	s_barrier
	s_mul_i32 s4, s10, 0xc000
	s_add_i32 s4, s4, 0
	v_add_u32_e32 v64, s4, v157
	v_add3_u32 v65, v64, s18, v169
	v_add3_u32 v64, v64, s17, v169
	v_add_u32_e32 v68, s4, v158
	ds_read_b128 v[124:127], v65
	ds_read_b128 v[120:123], v65 offset:2048
	ds_read_b128 v[100:103], v65 offset:4096
	ds_read_b128 v[96:99], v65 offset:6144
	ds_read_b128 v[108:111], v64 offset:32768
	ds_read_b128 v[112:115], v64 offset:34816
	ds_read_b128 v[116:119], v64 offset:36864
	ds_read_b128 v[104:107], v64 offset:38912
	v_add3_u32 v64, v68, s18, v169
	v_add3_u32 v68, v68, s17, v169
	ds_read_b128 v[92:95], v64
	ds_read_b128 v[88:91], v64 offset:2048
	ds_read_b128 v[72:75], v64 offset:4096
	ds_read_b128 v[64:67], v64 offset:6144
	ds_read_b128 v[76:79], v68 offset:32768
	ds_read_b128 v[80:83], v68 offset:34816
	ds_read_b128 v[84:87], v68 offset:36864
	ds_read_b128 v[68:71], v68 offset:38912
	s_waitcnt lgkmcnt(0)
	v_sub_co_u32_e64 v128, s[4:5], s10, 1
	s_and_b64 s[4:5], s[4:5], exec
	v_readfirstlane_b32 s4, v128
	s_cselect_b32 s13, 2, s4
	v_cndmask_b32_e64 v128, 0, 1, s[90:91]
	s_mov_b64 s[4:5], -1
	v_cmp_ne_u32_e64 s[6:7], 1, v128
	s_andn2_b64 vcc, exec, s[90:91]
	s_mul_i32 s12, s13, 0xc000
	s_cbranch_vccnz .LBB0_670
	s_mul_i32 s11, s13, 0xc000
	s_mov_b64 s[4:5], 0

.LBB0_1345:
	s_or_b64 exec, exec, s[6:7]
	v_readlane_b32 s0, v219, 52
	v_readlane_b32 s1, v219, 53
	s_andn2_b64 vcc, exec, s[0:1]
	v_readfirstlane_b32 s5, v168
	s_waitcnt lgkmcnt(0)
	s_barrier
	v_mov_b32_e32 v222, 0
	s_cbranch_vccnz .LBB0_1409
	s_add_u32 s0, s56, 0x1e80000
	s_addc_u32 s1, s57, 0
	s_lshl_b32 s2, s78, 19
	s_lshr_b32 s33, s5, 6
	s_bfe_u32 s38, s5, 0x10006
	s_lshr_b32 s39, s5, 7
	s_and_b32 s2, s2, 0xf80000
	s_add_u32 s4, s30, s2
	s_addc_u32 s21, s31, 0
	s_lshl_b32 s2, s78, 2
	s_and_b32 s2, s2, 0xffffff80
	s_ashr_i32 s3, s2, 31
	s_mov_b32 s73, 0
	s_lshl_b64 s[6:7], s[2:3], 11
	s_lshl_b32 s72, s33, 5
	s_lshl_b32 s2, s33, 12
	s_add_i32 s3, s2, 0
	s_lshl_b64 s[12:13], s[72:73], 11
	s_add_u32 s8, s4, s12
	s_addc_u32 s9, s21, s13
	s_or_b32 s10, s72, 8
	s_mov_b32 s11, s73
	s_lshl_b64 s[14:15], s[10:11], 11
	s_add_u32 s10, s4, s14
	v_mov_b32_e32 v0, v178
	v_mov_b32_e32 v1, v179
	s_mov_b32 m0, s3
	s_addc_u32 s11, s21, s15
	s_or_b32 s16, s72, 16
	s_mov_b32 s17, s73
	s_barrier
	s_lshl_b64 s[18:19], s[16:17], 11
	global_load_lds_dwordx4 v0, s[8:9]
	s_add_i32 m0, s3, 0x400
	s_add_u32 s16, s4, s18
	s_addc_u32 s17, s21, s19
	s_or_b32 s72, s72, 24
	global_load_lds_dwordx4 v1, s[10:11]
	s_add_i32 m0, s3, 0x800
	s_lshl_b64 s[22:23], s[72:73], 11
	s_add_u32 s20, s4, s22
	global_load_lds_dwordx4 v0, s[16:17]
	s_addc_u32 s21, s21, s23
	s_add_i32 m0, s3, 0xc00
	s_add_u32 s28, s0, s6
	s_addc_u32 s29, s1, s7
	s_lshl_b32 s4, s33, 11
	s_lshl_b32 s72, s33, 4
	s_sub_i32 s34, s3, s4
	global_load_lds_dwordx4 v1, s[20:21]
	s_add_i32 m0, s34, 0x8000
	s_lshl_b64 s[24:25], s[72:73], 11
	s_add_u32 s6, s28, s24
	s_addc_u32 s7, s29, s25
	s_or_b32 s72, s72, 8
	s_lshl_b64 s[26:27], s[72:73], 11
	s_add_u32 s28, s28, s26
	global_load_lds_dwordx4 v0, s[6:7]
	s_addc_u32 s29, s29, s27
	s_add_i32 m0, s34, 0x8400
	v_mov_b32_e32 v148, v178
	v_mov_b32_e32 v0, v179
	v_mov_b32_e32 v149, 0
	global_load_lds_dwordx4 v1, s[28:29]
	s_mov_b64 s[34:35], 0x80
	v_lshl_add_u64 v[2:3], s[8:9], 0, v[148:149]
	s_add_i32 m0, s3, 0xc000
	v_lshl_add_u64 v[2:3], v[2:3], 0, s[34:35]
	v_mov_b32_e32 v1, v149
	global_load_lds_dwordx4 v[2:3], off
	v_lshl_add_u64 v[2:3], s[10:11], 0, v[0:1]
	v_lshl_add_u64 v[2:3], v[2:3], 0, s[34:35]
	s_add_i32 m0, s3, 0xc400
	s_add_i32 s8, s4, 0
	global_load_lds_dwordx4 v[2:3], off
	v_lshl_add_u64 v[2:3], s[16:17], 0, v[148:149]
	v_lshl_add_u64 v[2:3], v[2:3], 0, s[34:35]
	s_add_i32 m0, s3, 0xc800
	v_readlane_b32 s10, v219, 33
	global_load_lds_dwordx4 v[2:3], off
	v_lshl_add_u64 v[2:3], s[20:21], 0, v[0:1]
	v_lshl_add_u64 v[2:3], v[2:3], 0, s[34:35]
	s_add_i32 m0, s3, 0xcc00
	v_lshl_add_u64 v[0:1], s[28:29], 0, v[0:1]
	global_load_lds_dwordx4 v[2:3], off
	v_lshl_add_u64 v[2:3], s[6:7], 0, v[148:149]
	s_add_i32 m0, s8, 0x14000
	v_lshl_add_u64 v[2:3], v[2:3], 0, s[34:35]
	global_load_lds_dwordx4 v[2:3], off
	v_lshl_add_u64 v[0:1], v[0:1], 0, s[34:35]
	s_add_i32 m0, s8, 0x14400
	s_cmpk_gt_u32 s5, 0xff
	global_load_lds_dwordx4 v[0:1], off
	s_cselect_b64 s[36:37], -1, 0
	s_lshl_b32 s72, s33, 15
	s_lshl_b32 s6, s33, 14
	s_lshl_b32 s5, s38, 13
	s_lshl_b32 s16, s39, 13
	s_lshl_b32 s8, s38, 6
	v_readlane_b32 s11, v219, 34
	s_add_u32 s8, s10, s8
	s_addc_u32 s9, s11, 0
	s_add_u32 s17, s56, s12
	s_addc_u32 s28, s57, s13
	s_lshl_b32 s29, s78, 8
	s_lshl_b32 s33, s58, 8
	s_add_u32 s76, s56, s24
	v_lshl_or_b32 v150, s39, 6, v167
	s_addc_u32 s77, s57, s25
	s_lshl_b64 s[38:39], s[72:73], 1
	s_mov_b32 s7, s73
	v_add_u32_e32 v0, 12, v146
	v_cmp_eq_u32_e32 vcc, 0, v171
	s_mov_b32 s83, s78
	s_add_u32 s78, s56, s38
	v_cndmask_b32_e32 v0, v0, v146, vcc
	v_xor_b32_e32 v1, v147, v170
	s_addc_u32 s79, s57, s39
	s_lshl_b64 s[40:41], s[6:7], 1
	v_lshlrev_b32_e32 v151, 4, v1
	v_bitop3_b32 v1, v147, v170, 4 bitop3:0x36
	v_lshlrev_b32_e32 v148, 1, v0
	s_add_u32 s80, s56, s40
	v_lshlrev_b32_e32 v152, 4, v1
	v_lshl_add_u64 v[146:147], s[8:9], 0, v[148:149]
	s_addc_u32 s81, s57, s41
	s_mov_b64 s[6:7], -1
	s_mov_b64 s[42:43], 0x100
	s_mov_b64 s[44:45], 0x3400180
	s_mov_b64 s[46:47], 0x3404180
	s_mov_b64 s[48:49], 0x3408180
	s_mov_b64 s[50:51], 0x340c180
	s_mov_b64 s[52:53], 0x1e80180
	s_mov_b64 s[60:61], 0x1e84180
	s_mov_b64 s[62:63], 0x4000
	s_mov_b64 s[64:65], 0x8000
	s_movk_i32 s82, 0x1600
	s_branch .LBB0_1348

.Lrw1356_d:
	s_barrier
	s_waitcnt lgkmcnt(0)
	v_mfma_f32_16x16x32_bf16 v[124:127], v[52:55], v[64:67], v[124:127]
	s_mul_i32 vcc_lo, s93, 0xc000
	s_add_i32 s96, vcc_lo, 0xffff4000
	v_mfma_f32_16x16x32_bf16 v[120:123], v[48:51], v[64:67], v[120:123]
	s_cmp_lg_u32 s93, 0
	s_cselect_b32 vcc_hi, s96, 0x18000
	s_add_i32 s66, s3, vcc_hi
	v_mfma_f32_16x16x32_bf16 v[116:119], v[44:47], v[64:67], v[116:119]
	v_mfma_f32_16x16x32_bf16 v[64:67], v[40:43], v[64:67], v[112:115]
	v_mfma_f32_16x16x32_bf16 v[108:111], v[52:55], v[56:59], v[108:111]
	v_mfma_f32_16x16x32_bf16 v[104:107], v[48:51], v[56:59], v[104:107]
	v_mfma_f32_16x16x32_bf16 v[100:103], v[44:47], v[56:59], v[100:103]
	v_mfma_f32_16x16x32_bf16 v[56:59], v[40:43], v[56:59], v[96:99]
	s_add_u32 s96, s10, s8
	v_mov_b32_e32 v148, v178
	s_addc_u32 s97, s11, s9
	s_mov_b32 m0, s66
	s_add_u32 s98, s96, s44
	s_addc_u32 s99, s97, s45
	global_load_lds_dwordx4 v178, s[98:99]
	v_mfma_f32_16x16x32_bf16 v[92:95], v[52:55], v[36:39], v[92:95]
	v_mfma_f32_16x16x32_bf16 v[88:91], v[48:51], v[36:39], v[88:91]
	v_mfma_f32_16x16x32_bf16 v[84:87], v[44:47], v[36:39], v[84:87]
	v_mfma_f32_16x16x32_bf16 v[36:39], v[40:43], v[36:39], v[80:83]
	v_mfma_f32_16x16x32_bf16 v[52:55], v[52:55], v[32:35], v[76:79]
	v_mfma_f32_16x16x32_bf16 v[48:51], v[48:51], v[32:35], v[72:75]
	v_mfma_f32_16x16x32_bf16 v[44:47], v[44:47], v[32:35], v[68:71]
	v_mfma_f32_16x16x32_bf16 v[32:35], v[40:43], v[32:35], v[60:63]
	v_mov_b32_e32 v148, v179
	s_add_i32 m0, s66, 0x400
	s_add_u32 s100, s96, s46
	s_addc_u32 s101, s97, s47
	global_load_lds_dwordx4 v179, s[100:101]
	v_mfma_f32_16x16x32_bf16 v[124:127], v[20:23], v[28:31], v[124:127]
	v_mfma_f32_16x16x32_bf16 v[120:123], v[16:19], v[28:31], v[120:123]
	v_mfma_f32_16x16x32_bf16 v[116:119], v[12:15], v[28:31], v[116:119]
	v_mfma_f32_16x16x32_bf16 v[112:115], v[8:11], v[28:31], v[64:67]
	v_mfma_f32_16x16x32_bf16 v[108:111], v[20:23], v[24:27], v[108:111]
	v_mfma_f32_16x16x32_bf16 v[104:107], v[16:19], v[24:27], v[104:107]
	v_mfma_f32_16x16x32_bf16 v[100:103], v[12:15], v[24:27], v[100:103]
	v_mfma_f32_16x16x32_bf16 v[96:99], v[8:11], v[24:27], v[56:59]
	v_mov_b32_e32 v148, v178
	s_add_i32 m0, s66, 0x800
	s_add_u32 s98, s96, s48
	s_addc_u32 s99, s97, s49
	global_load_lds_dwordx4 v178, s[98:99]
	v_mfma_f32_16x16x32_bf16 v[92:95], v[20:23], v[4:7], v[92:95]
	s_waitcnt lgkmcnt(0)
	v_mfma_f32_16x16x32_bf16 v[88:91], v[16:19], v[4:7], v[88:91]
	v_mfma_f32_16x16x32_bf16 v[84:87], v[12:15], v[4:7], v[84:87]
	v_mfma_f32_16x16x32_bf16 v[80:83], v[8:11], v[4:7], v[36:39]
	v_mfma_f32_16x16x32_bf16 v[76:79], v[20:23], v[0:3], v[52:55]
	v_mfma_f32_16x16x32_bf16 v[72:75], v[16:19], v[0:3], v[48:51]
	v_mfma_f32_16x16x32_bf16 v[68:71], v[12:15], v[0:3], v[44:47]
	v_mfma_f32_16x16x32_bf16 v[60:63], v[8:11], v[0:3], v[32:35]
	s_barrier
	s_add_i32 s66, vcc_lo, 0
	v_add_u32_e32 v0, s66, v151
	v_add_u32_e32 v8, s66, v152
	s_add_i32 s66, vcc_hi, 0
	s_add_i32 s67, s66, s2
	s_add_i32 m0, s67, 0xc00
	s_add_u32 s100, s96, s50
	s_addc_u32 s101, s97, s51
	s_add_u32 s96, s94, s8
	s_addc_u32 s97, s95, s9
	global_load_lds_dwordx4 v179, s[100:101]
	s_add_i32 s66, s66, s4
	s_add_i32 m0, s66, 0x8000
	s_add_u32 s98, s96, s52
	s_addc_u32 s99, s97, s53
	global_load_lds_dwordx4 v178, s[98:99]
	s_add_i32 m0, s66, 0x8400
	s_add_u32 s100, s96, s60
	s_addc_u32 s101, s97, s61
	global_load_lds_dwordx4 v179, s[100:101]
	v_add3_u32 v1, v0, s16, v169
	v_add3_u32 v0, v0, s5, v169
	ds_read_b128 v[64:67], v1
	ds_read_b128 v[56:59], v1 offset:2048
	ds_read_b128 v[36:39], v1 offset:4096
	ds_read_b128 v[32:35], v1 offset:6144
	ds_read_b128 v[52:55], v0 offset:32768
	ds_read_b128 v[48:51], v0 offset:34816
	ds_read_b128 v[44:47], v0 offset:36864
	ds_read_b128 v[40:43], v0 offset:38912
	v_add3_u32 v0, v8, s16, v169
	v_add3_u32 v8, v8, s5, v169
	ds_read_b128 v[28:31], v0
	ds_read_b128 v[24:27], v0 offset:2048
	ds_read_b128 v[4:7], v0 offset:4096
	ds_read_b128 v[0:3], v0 offset:6144
	ds_read_b128 v[20:23], v8 offset:32768
	ds_read_b128 v[16:19], v8 offset:34816
	ds_read_b128 v[12:15], v8 offset:36864
	ds_read_b128 v[8:11], v8 offset:38912
	s_waitcnt lgkmcnt(0)
	v_mov_b32_e32 v148, v179
	v_mov_b32_e32 v148, v178
	v_mov_b32_e32 v148, v179
	s_add_i32 s66, s93, 1
	s_cmp_lg_u32 s93, 2
	s_cselect_b32 s93, s66, 0
	s_add_u32 s8, s8, 0x80
	s_addc_u32 s9, s9, 0
	s_cmpk_eq_i32 s8, 0x680
	s_cbranch_scc0 .LBB0_1356
	v_mov_b32_e32 v222, 1
	s_waitcnt vmcnt(6) lgkmcnt(0)
	s_barrier
	s_waitcnt lgkmcnt(0)
	v_mfma_f32_16x16x32_bf16 v[124:127], v[52:55], v[64:67], v[124:127]
	s_mul_i32 s11, s93, 0xc000
	s_add_i32 s8, s11, 0xffff4000
	v_mfma_f32_16x16x32_bf16 v[120:123], v[48:51], v[64:67], v[120:123]
	s_cmp_lg_u32 s93, 0
	s_cselect_b32 s10, s8, 0x18000
	s_andn2_b64 vcc, exec, s[70:71]
	v_mfma_f32_16x16x32_bf16 v[116:119], v[44:47], v[64:67], v[116:119]
	v_mfma_f32_16x16x32_bf16 v[64:67], v[40:43], v[64:67], v[112:115]
	v_mfma_f32_16x16x32_bf16 v[108:111], v[52:55], v[56:59], v[108:111]
	s_nop 1
	v_cndmask_b32_e64 v112, 0, 1, s[70:71]
	v_cmp_ne_u32_e64 s[8:9], 1, v112
	v_mfma_f32_16x16x32_bf16 v[104:107], v[48:51], v[56:59], v[104:107]
	v_mfma_f32_16x16x32_bf16 v[100:103], v[44:47], v[56:59], v[100:103]
	v_mfma_f32_16x16x32_bf16 v[140:143], v[40:43], v[56:59], v[96:99]
	s_cbranch_vccnz .LBB0_1359
	s_add_u32 s94, s86, s12
	v_mov_b32_e32 v56, v178
	s_addc_u32 s95, s87, s13
	s_add_i32 m0, s3, s10
	s_nop 0
	global_load_lds_dwordx4 v56, s[94:95]

.Lrw1383_d:
	s_barrier
	s_mul_i32 s73, s10, 0xc000
	s_add_i32 s74, s73, 0
	v_add_u32_e32 v80, s74, v151
	v_add_u32_e32 v112, s74, v152
	s_add_i32 s73, s73, 0xffff4000
	s_cmp_lg_u32 s10, 0
	s_cselect_b32 s73, s73, 0x18000
	s_add_i32 s90, s73, 0
	s_add_u32 s74, s8, s6
	s_addc_u32 s75, s9, s7
	s_add_i32 s88, s90, s2
	s_add_i32 m0, s88, 0xc00
	s_add_u32 s88, s11, s6
	s_addc_u32 s89, s72, s7
	s_add_u32 s98, s74, s50
	s_addc_u32 s99, s75, s51
	global_load_lds_dwordx4 v179, s[98:99]
	s_add_i32 s90, s90, s4
	s_add_i32 m0, s90, 0x8000
	s_add_u32 s100, s88, s52
	s_addc_u32 s101, s89, s53
	global_load_lds_dwordx4 v178, s[100:101]
	s_add_i32 m0, s90, 0x8400
	s_add_u32 s98, s88, s60
	s_addc_u32 s99, s89, s61
	global_load_lds_dwordx4 v179, s[98:99]
	v_add3_u32 v76, v80, s16, v169
	v_add3_u32 v92, v80, s5, v169
	v_add3_u32 v108, v112, s16, v169
	v_add3_u32 v124, v112, s5, v169
	ds_read_b128 v[64:67], v76
	ds_read_b128 v[68:71], v76 offset:2048
	ds_read_b128 v[72:75], v76 offset:4096
	ds_read_b128 v[76:79], v76 offset:6144
	ds_read_b128 v[80:83], v92 offset:32768
	ds_read_b128 v[84:87], v92 offset:34816
	ds_read_b128 v[88:91], v92 offset:36864
	ds_read_b128 v[92:95], v92 offset:38912
	ds_read_b128 v[96:99], v108
	ds_read_b128 v[100:103], v108 offset:2048
	ds_read_b128 v[104:107], v108 offset:4096
	ds_read_b128 v[108:111], v108 offset:6144
	ds_read_b128 v[112:115], v124 offset:32768
	ds_read_b128 v[116:119], v124 offset:34816
	ds_read_b128 v[120:123], v124 offset:36864
	ds_read_b128 v[124:127], v124 offset:38912
	s_waitcnt lgkmcnt(0)
	v_mov_b32_e32 v148, v179
	v_mov_b32_e32 v148, v178
	v_mov_b32_e32 v148, v179
	s_waitcnt lgkmcnt(0)
	s_barrier
	s_waitcnt lgkmcnt(0)
	v_mfma_f32_16x16x32_bf16 v[60:63], v[80:83], v[64:67], v[60:63]
	s_add_i32 s73, s3, s73
	v_mfma_f32_16x16x32_bf16 v[56:59], v[84:87], v[64:67], v[56:59]
	v_mfma_f32_16x16x32_bf16 v[52:55], v[88:91], v[64:67], v[52:55]
	v_mfma_f32_16x16x32_bf16 v[48:51], v[92:95], v[64:67], v[48:51]
	v_mfma_f32_16x16x32_bf16 v[44:47], v[80:83], v[68:71], v[44:47]
	v_mfma_f32_16x16x32_bf16 v[40:43], v[84:87], v[68:71], v[40:43]
	v_mfma_f32_16x16x32_bf16 v[36:39], v[88:91], v[68:71], v[36:39]
	v_mfma_f32_16x16x32_bf16 v[24:27], v[92:95], v[68:71], v[24:27]
	v_mov_b32_e32 v148, v178
	s_mov_b32 m0, s73
	s_add_u32 s100, s74, s44
	s_addc_u32 s101, s75, s45
	global_load_lds_dwordx4 v178, s[100:101]
	v_mfma_f32_16x16x32_bf16 v[20:23], v[80:83], v[72:75], v[20:23]
	v_mfma_f32_16x16x32_bf16 v[16:19], v[84:87], v[72:75], v[16:19]
	v_mfma_f32_16x16x32_bf16 v[12:15], v[88:91], v[72:75], v[12:15]
	v_mfma_f32_16x16x32_bf16 v[8:11], v[92:95], v[72:75], v[8:11]
	v_mfma_f32_16x16x32_bf16 v[4:7], v[80:83], v[76:79], v[4:7]
	v_mfma_f32_16x16x32_bf16 v[0:3], v[84:87], v[76:79], v[0:3]
	v_mfma_f32_16x16x32_bf16 v[28:31], v[88:91], v[76:79], v[28:31]
	v_mfma_f32_16x16x32_bf16 v[32:35], v[92:95], v[76:79], v[32:35]
	v_mov_b32_e32 v148, v179
	s_add_i32 m0, s73, 0x400
	s_add_u32 s98, s74, s46
	s_addc_u32 s99, s75, s47
	global_load_lds_dwordx4 v179, s[98:99]
	v_mfma_f32_16x16x32_bf16 v[60:63], v[112:115], v[96:99], v[60:63]
	v_mfma_f32_16x16x32_bf16 v[56:59], v[116:119], v[96:99], v[56:59]
	v_mfma_f32_16x16x32_bf16 v[52:55], v[120:123], v[96:99], v[52:55]
	v_mfma_f32_16x16x32_bf16 v[48:51], v[124:127], v[96:99], v[48:51]
	v_mfma_f32_16x16x32_bf16 v[44:47], v[112:115], v[100:103], v[44:47]
	v_mfma_f32_16x16x32_bf16 v[40:43], v[116:119], v[100:103], v[40:43]
	v_mfma_f32_16x16x32_bf16 v[36:39], v[120:123], v[100:103], v[36:39]
	v_mfma_f32_16x16x32_bf16 v[24:27], v[124:127], v[100:103], v[24:27]
	v_mov_b32_e32 v148, v178
	s_add_i32 m0, s73, 0x800
	s_add_u32 s100, s74, s48
	s_addc_u32 s101, s75, s49
	global_load_lds_dwordx4 v178, s[100:101]
	s_add_i32 s73, s10, 1
	v_mfma_f32_16x16x32_bf16 v[20:23], v[112:115], v[104:107], v[20:23]
	s_cmp_lg_u32 s10, 2
	s_cselect_b32 s10, s73, 0
	s_add_u32 s6, s6, 0x80
	v_mfma_f32_16x16x32_bf16 v[16:19], v[116:119], v[104:107], v[16:19]
	s_addc_u32 s7, s7, 0
	s_cmpk_eq_i32 s6, 0x680
	v_mfma_f32_16x16x32_bf16 v[12:15], v[120:123], v[104:107], v[12:15]
	v_mfma_f32_16x16x32_bf16 v[8:11], v[124:127], v[104:107], v[8:11]
	v_mfma_f32_16x16x32_bf16 v[4:7], v[112:115], v[108:111], v[4:7]
	v_mfma_f32_16x16x32_bf16 v[0:3], v[116:119], v[108:111], v[0:3]
	v_mfma_f32_16x16x32_bf16 v[28:31], v[120:123], v[108:111], v[28:31]
	v_mfma_f32_16x16x32_bf16 v[32:35], v[124:127], v[108:111], v[32:35]
	s_cbranch_scc0 .LBB0_1383
	v_mov_b32_e32 v222, 1
	s_waitcnt vmcnt(6) lgkmcnt(0)
	s_barrier
	s_mul_i32 s6, s10, 0xc000
	s_add_i32 s6, s6, 0
	v_add_u32_e32 v64, s6, v151
	v_add3_u32 v65, v64, s16, v169
	v_add3_u32 v64, v64, s5, v169
	v_add_u32_e32 v68, s6, v152
	ds_read_b128 v[124:127], v65
	ds_read_b128 v[120:123], v65 offset:2048
	ds_read_b128 v[100:103], v65 offset:4096
	ds_read_b128 v[96:99], v65 offset:6144
	ds_read_b128 v[108:111], v64 offset:32768
	ds_read_b128 v[112:115], v64 offset:34816
	ds_read_b128 v[116:119], v64 offset:36864
	ds_read_b128 v[104:107], v64 offset:38912
	v_add3_u32 v64, v68, s16, v169
	v_add3_u32 v68, v68, s5, v169
	ds_read_b128 v[92:95], v64
	ds_read_b128 v[88:91], v64 offset:2048
	ds_read_b128 v[72:75], v64 offset:4096
	ds_read_b128 v[64:67], v64 offset:6144
	ds_read_b128 v[76:79], v68 offset:32768
	ds_read_b128 v[80:83], v68 offset:34816
	ds_read_b128 v[84:87], v68 offset:36864
	ds_read_b128 v[68:71], v68 offset:38912
	s_waitcnt lgkmcnt(0)
	v_sub_co_u32_e64 v128, s[6:7], s10, 1
	s_and_b64 s[6:7], s[6:7], exec
	v_readfirstlane_b32 s6, v128
	s_cselect_b32 s73, 2, s6
	v_cndmask_b32_e64 v128, 0, 1, s[68:69]
	s_mov_b64 s[6:7], -1
	v_cmp_ne_u32_e64 s[8:9], 1, v128
	s_andn2_b64 vcc, exec, s[68:69]
	s_mul_i32 s72, s73, 0xc000
	s_cbranch_vccnz .LBB0_1386
	s_mul_i32 s11, s73, 0xc000
	s_mov_b64 s[6:7], 0
